# every LDS instruction of the recurrence loop sits behind a non-VALU slot
# speedup vs baseline: 1.0135x; 1.0032x over previous
.LBB0_682:
	s_bitcmp1_b32 s30, 0
	s_cselect_b32 s6, 0xe000, 0
	s_add_i32 s6, s6, 0
	v_add_u32_e32 v90, s6, v58
	v_sub_u32_e32 v88, v90, v61
	v_add_u32_e32 v89, s6, v86
	ds_read_b128 v[4:7], v90 offset:0x4000
	ds_read_b128 v[8:11], v90 offset:0x0
	ds_read2st64_b32 v[108:109], v89 offset0:192 offset1:193
	ds_read2st64_b64 v[100:103], v88 offset0:64 offset1:65
	ds_read_b128 v[112:115], v90 offset:0x4200
	ds_read_b128 v[96:99], v90 offset:0x200
	ds_read_b128 v[120:123], v90 offset:0x4400
	ds_read_b128 v[124:127], v90 offset:0x400
	v_mov_b32_e32 v93, v91
	s_waitcnt lgkmcnt(5)
	v_pk_mul_f32 v[0:1], v[52:53], v[4:5] op_sel_hi:[0,1]
	v_pk_fma_f32 v[0:1], v[52:53], v[6:7], v[0:1] op_sel:[1,0,0]
	v_pk_mul_f32 v[10:11], v[108:109], v[10:11] op_sel_hi:[0,1]
	v_pk_fma_f32 v[54:55], v[52:53], v[8:9], v[10:11]
	v_add_f32_dpp v0, v0, v0 quad_perm:[1,0,3,2] row_mask:0xf bank_mask:0xf bound_ctrl:1
	v_add_f32_dpp v1, v1, v1 quad_perm:[1,0,3,2] row_mask:0xf bank_mask:0xf bound_ctrl:1
	s_nop 0
	ds_read_b128 v[4:7], v90 offset:0x4600
	v_add_f32_dpp v0, v0, v0 quad_perm:[2,3,0,1] row_mask:0xf bank_mask:0xf bound_ctrl:1
	s_nop 0
	ds_read_b128 v[8:11], v90 offset:0x600
	v_add_f32_dpp v0, v0, v0 row_half_mirror row_mask:0xf bank_mask:0xf bound_ctrl:1
	s_nop 0
	ds_read2st64_b32 v[110:111], v89 offset0:194 offset1:195
	ds_read2st64_b64 v[104:107], v88 offset0:66 offset1:67
	v_add_f32_dpp v2, v0, v0 row_mirror row_mask:0xf bank_mask:0xf bound_ctrl:1
	v_add_f32_dpp v0, v0, v0 row_mirror row_mask:0xf bank_mask:0xf bound_ctrl:1
	s_nop 0
	s_waitcnt lgkmcnt(6)
	v_permlane16_swap_b32_e32 v0, v2
	v_add_f32_e32 v0, v0, v2
	v_pk_fma_f32 v[52:53], v[100:101], v[0:1], v[54:55] op_sel_hi:[1,0,1]
	v_pk_mul_f32 v[118:119], v[52:53], v[112:113] op_sel_hi:[0,1]
	v_pk_fma_f32 v[118:119], v[52:53], v[114:115], v[118:119] op_sel:[1,0,0]
	v_pk_mul_f32 v[98:99], v[108:109], v[98:99] op_sel:[1,0]
	v_pk_fma_f32 v[54:55], v[52:53], v[96:97], v[98:99]
	v_add_f32_dpp v118, v118, v118 quad_perm:[1,0,3,2] row_mask:0xf bank_mask:0xf bound_ctrl:1
	v_add_f32_dpp v119, v119, v119 quad_perm:[1,0,3,2] row_mask:0xf bank_mask:0xf bound_ctrl:1
	s_nop 0
	ds_read_b128 v[112:115], v90 offset:0x4800
	v_add_f32_dpp v118, v118, v118 quad_perm:[2,3,0,1] row_mask:0xf bank_mask:0xf bound_ctrl:1
	s_nop 0
	ds_read_b128 v[96:99], v90 offset:0x800
	v_add_f32_dpp v118, v118, v118 row_half_mirror row_mask:0xf bank_mask:0xf bound_ctrl:1
	s_nop 0
	ds_write2_b32 v93, v1, v119 offset0:0 offset1:36
	v_add_f32_dpp v2, v118, v118 row_mirror row_mask:0xf bank_mask:0xf bound_ctrl:1
	v_add_f32_dpp v118, v118, v118 row_mirror row_mask:0xf bank_mask:0xf bound_ctrl:1
	s_nop 0
	s_waitcnt lgkmcnt(4)
	v_permlane16_swap_b32_e32 v118, v2
	v_add_f32_e32 v118, v118, v2
	v_pk_fma_f32 v[52:53], v[102:103], v[118:119], v[54:55] op_sel_hi:[1,0,1]
	v_pk_mul_f32 v[0:1], v[52:53], v[120:121] op_sel_hi:[0,1]
	v_pk_fma_f32 v[0:1], v[52:53], v[122:123], v[0:1] op_sel:[1,0,0]
	v_pk_mul_f32 v[126:127], v[110:111], v[126:127] op_sel_hi:[0,1]
	v_pk_fma_f32 v[54:55], v[52:53], v[124:125], v[126:127]
	v_add_f32_dpp v0, v0, v0 quad_perm:[1,0,3,2] row_mask:0xf bank_mask:0xf bound_ctrl:1
	v_add_f32_dpp v1, v1, v1 quad_perm:[1,0,3,2] row_mask:0xf bank_mask:0xf bound_ctrl:1
	s_nop 0
	ds_read_b128 v[120:123], v90 offset:0x4a00
	v_add_f32_dpp v0, v0, v0 quad_perm:[2,3,0,1] row_mask:0xf bank_mask:0xf bound_ctrl:1
	s_nop 0
	ds_read_b128 v[124:127], v90 offset:0xa00
	v_add_f32_dpp v0, v0, v0 row_half_mirror row_mask:0xf bank_mask:0xf bound_ctrl:1
	s_nop 0
	ds_read2st64_b32 v[108:109], v89 offset0:196 offset1:197
	ds_read2st64_b64 v[100:103], v88 offset0:68 offset1:69
	v_add_f32_dpp v2, v0, v0 row_mirror row_mask:0xf bank_mask:0xf bound_ctrl:1
	v_add_f32_dpp v0, v0, v0 row_mirror row_mask:0xf bank_mask:0xf bound_ctrl:1
	s_nop 0
	s_waitcnt lgkmcnt(7)
	v_permlane16_swap_b32_e32 v0, v2
	v_add_f32_e32 v0, v0, v2
	v_pk_fma_f32 v[52:53], v[104:105], v[0:1], v[54:55] op_sel_hi:[1,0,1]
	v_pk_mul_f32 v[118:119], v[52:53], v[4:5] op_sel_hi:[0,1]
	v_pk_fma_f32 v[118:119], v[52:53], v[6:7], v[118:119] op_sel:[1,0,0]
	v_pk_mul_f32 v[10:11], v[110:111], v[10:11] op_sel:[1,0]
	v_pk_fma_f32 v[54:55], v[52:53], v[8:9], v[10:11]
	v_add_f32_dpp v118, v118, v118 quad_perm:[1,0,3,2] row_mask:0xf bank_mask:0xf bound_ctrl:1
	v_add_f32_dpp v119, v119, v119 quad_perm:[1,0,3,2] row_mask:0xf bank_mask:0xf bound_ctrl:1
	s_nop 0
	ds_read_b128 v[4:7], v90 offset:0x4c00
	v_add_f32_dpp v118, v118, v118 quad_perm:[2,3,0,1] row_mask:0xf bank_mask:0xf bound_ctrl:1
	s_nop 0
	ds_read_b128 v[8:11], v90 offset:0xc00
	v_add_f32_dpp v118, v118, v118 row_half_mirror row_mask:0xf bank_mask:0xf bound_ctrl:1
	s_nop 0
	ds_write2_b32 v93, v1, v119 offset0:72 offset1:108
	v_add_f32_dpp v2, v118, v118 row_mirror row_mask:0xf bank_mask:0xf bound_ctrl:1
	v_add_f32_dpp v118, v118, v118 row_mirror row_mask:0xf bank_mask:0xf bound_ctrl:1
	s_nop 0
	s_waitcnt lgkmcnt(4)
	v_permlane16_swap_b32_e32 v118, v2
	v_add_f32_e32 v118, v118, v2
	v_pk_fma_f32 v[52:53], v[106:107], v[118:119], v[54:55] op_sel_hi:[1,0,1]
	v_pk_mul_f32 v[0:1], v[52:53], v[112:113] op_sel_hi:[0,1]
	v_pk_fma_f32 v[0:1], v[52:53], v[114:115], v[0:1] op_sel:[1,0,0]
	v_pk_mul_f32 v[98:99], v[108:109], v[98:99] op_sel_hi:[0,1]
	v_pk_fma_f32 v[54:55], v[52:53], v[96:97], v[98:99]
	v_add_f32_dpp v0, v0, v0 quad_perm:[1,0,3,2] row_mask:0xf bank_mask:0xf bound_ctrl:1
	v_add_f32_dpp v1, v1, v1 quad_perm:[1,0,3,2] row_mask:0xf bank_mask:0xf bound_ctrl:1
	s_nop 0
	ds_read_b128 v[112:115], v90 offset:0x4e00
	v_add_f32_dpp v0, v0, v0 quad_perm:[2,3,0,1] row_mask:0xf bank_mask:0xf bound_ctrl:1
	s_nop 0
	ds_read_b128 v[96:99], v90 offset:0xe00
	v_add_f32_dpp v0, v0, v0 row_half_mirror row_mask:0xf bank_mask:0xf bound_ctrl:1
	s_nop 0
	ds_read2st64_b32 v[110:111], v89 offset0:198 offset1:199
	ds_read2st64_b64 v[104:107], v88 offset0:70 offset1:71
	v_add_f32_dpp v2, v0, v0 row_mirror row_mask:0xf bank_mask:0xf bound_ctrl:1
	v_add_f32_dpp v0, v0, v0 row_mirror row_mask:0xf bank_mask:0xf bound_ctrl:1
	s_nop 0
	s_waitcnt lgkmcnt(7)
	v_permlane16_swap_b32_e32 v0, v2
	v_add_f32_e32 v0, v0, v2
	v_pk_fma_f32 v[52:53], v[100:101], v[0:1], v[54:55] op_sel_hi:[1,0,1]
	v_pk_mul_f32 v[118:119], v[52:53], v[120:121] op_sel_hi:[0,1]
	v_pk_fma_f32 v[118:119], v[52:53], v[122:123], v[118:119] op_sel:[1,0,0]
	v_pk_mul_f32 v[126:127], v[108:109], v[126:127] op_sel:[1,0]
	v_pk_fma_f32 v[54:55], v[52:53], v[124:125], v[126:127]
	v_add_f32_dpp v118, v118, v118 quad_perm:[1,0,3,2] row_mask:0xf bank_mask:0xf bound_ctrl:1
	v_add_f32_dpp v119, v119, v119 quad_perm:[1,0,3,2] row_mask:0xf bank_mask:0xf bound_ctrl:1
	s_nop 0
	ds_read_b128 v[120:123], v90 offset:0x5000
	v_add_f32_dpp v118, v118, v118 quad_perm:[2,3,0,1] row_mask:0xf bank_mask:0xf bound_ctrl:1
	s_nop 0
	ds_read_b128 v[124:127], v90 offset:0x1000
	v_add_f32_dpp v118, v118, v118 row_half_mirror row_mask:0xf bank_mask:0xf bound_ctrl:1
	s_nop 0
	ds_write2_b32 v93, v1, v119 offset0:144 offset1:180
	v_add_f32_dpp v2, v118, v118 row_mirror row_mask:0xf bank_mask:0xf bound_ctrl:1
	v_add_f32_dpp v118, v118, v118 row_mirror row_mask:0xf bank_mask:0xf bound_ctrl:1
	s_nop 0
	s_waitcnt lgkmcnt(4)
	v_permlane16_swap_b32_e32 v118, v2
	v_add_f32_e32 v118, v118, v2
	v_pk_fma_f32 v[52:53], v[102:103], v[118:119], v[54:55] op_sel_hi:[1,0,1]
	v_pk_mul_f32 v[0:1], v[52:53], v[4:5] op_sel_hi:[0,1]
	v_pk_fma_f32 v[0:1], v[52:53], v[6:7], v[0:1] op_sel:[1,0,0]
	v_pk_mul_f32 v[10:11], v[110:111], v[10:11] op_sel_hi:[0,1]
	v_pk_fma_f32 v[54:55], v[52:53], v[8:9], v[10:11]
	v_add_f32_dpp v0, v0, v0 quad_perm:[1,0,3,2] row_mask:0xf bank_mask:0xf bound_ctrl:1
	v_add_f32_dpp v1, v1, v1 quad_perm:[1,0,3,2] row_mask:0xf bank_mask:0xf bound_ctrl:1
	s_nop 0
	ds_read_b128 v[4:7], v90 offset:0x5200
	v_add_f32_dpp v0, v0, v0 quad_perm:[2,3,0,1] row_mask:0xf bank_mask:0xf bound_ctrl:1
	s_nop 0
	ds_read_b128 v[8:11], v90 offset:0x1200
	v_add_f32_dpp v0, v0, v0 row_half_mirror row_mask:0xf bank_mask:0xf bound_ctrl:1
	s_nop 0
	ds_read2st64_b32 v[108:109], v89 offset0:200 offset1:201
	ds_read2st64_b64 v[100:103], v88 offset0:72 offset1:73
	v_add_f32_dpp v2, v0, v0 row_mirror row_mask:0xf bank_mask:0xf bound_ctrl:1
	v_add_f32_dpp v0, v0, v0 row_mirror row_mask:0xf bank_mask:0xf bound_ctrl:1
	s_nop 0
	s_waitcnt lgkmcnt(7)
	v_permlane16_swap_b32_e32 v0, v2
	v_add_f32_e32 v0, v0, v2
	v_pk_fma_f32 v[52:53], v[104:105], v[0:1], v[54:55] op_sel_hi:[1,0,1]
	v_pk_mul_f32 v[118:119], v[52:53], v[112:113] op_sel_hi:[0,1]
	v_pk_fma_f32 v[118:119], v[52:53], v[114:115], v[118:119] op_sel:[1,0,0]
	v_pk_mul_f32 v[98:99], v[110:111], v[98:99] op_sel:[1,0]
	v_pk_fma_f32 v[54:55], v[52:53], v[96:97], v[98:99]
	v_add_f32_dpp v118, v118, v118 quad_perm:[1,0,3,2] row_mask:0xf bank_mask:0xf bound_ctrl:1
	v_add_f32_dpp v119, v119, v119 quad_perm:[1,0,3,2] row_mask:0xf bank_mask:0xf bound_ctrl:1
	s_nop 0
	ds_read_b128 v[112:115], v90 offset:0x5400
	v_add_f32_dpp v118, v118, v118 quad_perm:[2,3,0,1] row_mask:0xf bank_mask:0xf bound_ctrl:1
	s_nop 0
	ds_read_b128 v[96:99], v90 offset:0x1400
	v_add_f32_dpp v118, v118, v118 row_half_mirror row_mask:0xf bank_mask:0xf bound_ctrl:1
	s_nop 0
	ds_write2_b32 v93, v1, v119 offset0:216 offset1:252
	v_add_f32_dpp v2, v118, v118 row_mirror row_mask:0xf bank_mask:0xf bound_ctrl:1
	v_add_f32_dpp v118, v118, v118 row_mirror row_mask:0xf bank_mask:0xf bound_ctrl:1
	s_nop 0
	s_waitcnt lgkmcnt(4)
	v_permlane16_swap_b32_e32 v118, v2
	v_add_f32_e32 v118, v118, v2
	v_pk_fma_f32 v[52:53], v[106:107], v[118:119], v[54:55] op_sel_hi:[1,0,1]
	v_pk_mul_f32 v[0:1], v[52:53], v[120:121] op_sel_hi:[0,1]
	v_pk_fma_f32 v[0:1], v[52:53], v[122:123], v[0:1] op_sel:[1,0,0]
	v_pk_mul_f32 v[126:127], v[108:109], v[126:127] op_sel_hi:[0,1]
	v_pk_fma_f32 v[54:55], v[52:53], v[124:125], v[126:127]
	v_add_f32_dpp v0, v0, v0 quad_perm:[1,0,3,2] row_mask:0xf bank_mask:0xf bound_ctrl:1
	v_add_f32_dpp v1, v1, v1 quad_perm:[1,0,3,2] row_mask:0xf bank_mask:0xf bound_ctrl:1
	s_nop 0
	ds_read_b128 v[120:123], v90 offset:0x5600
	v_add_f32_dpp v0, v0, v0 quad_perm:[2,3,0,1] row_mask:0xf bank_mask:0xf bound_ctrl:1
	s_nop 0
	ds_read_b128 v[124:127], v90 offset:0x1600
	v_add_f32_dpp v0, v0, v0 row_half_mirror row_mask:0xf bank_mask:0xf bound_ctrl:1
	s_nop 0
	ds_read2st64_b32 v[110:111], v89 offset0:202 offset1:203
	ds_read2st64_b64 v[104:107], v88 offset0:74 offset1:75
	v_add_f32_dpp v2, v0, v0 row_mirror row_mask:0xf bank_mask:0xf bound_ctrl:1
	v_add_f32_dpp v0, v0, v0 row_mirror row_mask:0xf bank_mask:0xf bound_ctrl:1
	v_add_u32_e32 v93, 0x480, v93
	s_waitcnt lgkmcnt(7)
	v_permlane16_swap_b32_e32 v0, v2
	v_add_f32_e32 v0, v0, v2
	v_pk_fma_f32 v[52:53], v[100:101], v[0:1], v[54:55] op_sel_hi:[1,0,1]
	v_pk_mul_f32 v[118:119], v[52:53], v[4:5] op_sel_hi:[0,1]
	v_pk_fma_f32 v[118:119], v[52:53], v[6:7], v[118:119] op_sel:[1,0,0]
	v_pk_mul_f32 v[10:11], v[108:109], v[10:11] op_sel:[1,0]
	v_pk_fma_f32 v[54:55], v[52:53], v[8:9], v[10:11]
	v_add_f32_dpp v118, v118, v118 quad_perm:[1,0,3,2] row_mask:0xf bank_mask:0xf bound_ctrl:1
	v_add_f32_dpp v119, v119, v119 quad_perm:[1,0,3,2] row_mask:0xf bank_mask:0xf bound_ctrl:1
	s_nop 0
	ds_read_b128 v[4:7], v90 offset:0x5800
	v_add_f32_dpp v118, v118, v118 quad_perm:[2,3,0,1] row_mask:0xf bank_mask:0xf bound_ctrl:1
	s_nop 0
	ds_read_b128 v[8:11], v90 offset:0x1800
	v_add_f32_dpp v118, v118, v118 row_half_mirror row_mask:0xf bank_mask:0xf bound_ctrl:1
	s_nop 0
	ds_write2_b32 v93, v1, v119 offset0:0 offset1:36
	v_add_f32_dpp v2, v118, v118 row_mirror row_mask:0xf bank_mask:0xf bound_ctrl:1
	v_add_f32_dpp v118, v118, v118 row_mirror row_mask:0xf bank_mask:0xf bound_ctrl:1
	s_nop 0
	s_waitcnt lgkmcnt(4)
	v_permlane16_swap_b32_e32 v118, v2
	v_add_f32_e32 v118, v118, v2
	v_pk_fma_f32 v[52:53], v[102:103], v[118:119], v[54:55] op_sel_hi:[1,0,1]
	v_pk_mul_f32 v[0:1], v[52:53], v[112:113] op_sel_hi:[0,1]
	v_pk_fma_f32 v[0:1], v[52:53], v[114:115], v[0:1] op_sel:[1,0,0]
	v_pk_mul_f32 v[98:99], v[110:111], v[98:99] op_sel_hi:[0,1]
	v_pk_fma_f32 v[54:55], v[52:53], v[96:97], v[98:99]
	v_add_f32_dpp v0, v0, v0 quad_perm:[1,0,3,2] row_mask:0xf bank_mask:0xf bound_ctrl:1
	v_add_f32_dpp v1, v1, v1 quad_perm:[1,0,3,2] row_mask:0xf bank_mask:0xf bound_ctrl:1
	s_nop 0
	ds_read_b128 v[112:115], v90 offset:0x5a00
	v_add_f32_dpp v0, v0, v0 quad_perm:[2,3,0,1] row_mask:0xf bank_mask:0xf bound_ctrl:1
	s_nop 0
	ds_read_b128 v[96:99], v90 offset:0x1a00
	v_add_f32_dpp v0, v0, v0 row_half_mirror row_mask:0xf bank_mask:0xf bound_ctrl:1
	s_nop 0
	ds_read2st64_b32 v[108:109], v89 offset0:204 offset1:205
	ds_read2st64_b64 v[100:103], v88 offset0:76 offset1:77
	v_add_f32_dpp v2, v0, v0 row_mirror row_mask:0xf bank_mask:0xf bound_ctrl:1
	v_add_f32_dpp v0, v0, v0 row_mirror row_mask:0xf bank_mask:0xf bound_ctrl:1
	s_nop 0
	s_waitcnt lgkmcnt(7)
	v_permlane16_swap_b32_e32 v0, v2
	v_add_f32_e32 v0, v0, v2
	v_pk_fma_f32 v[52:53], v[104:105], v[0:1], v[54:55] op_sel_hi:[1,0,1]
	v_pk_mul_f32 v[118:119], v[52:53], v[120:121] op_sel_hi:[0,1]
	v_pk_fma_f32 v[118:119], v[52:53], v[122:123], v[118:119] op_sel:[1,0,0]
	v_pk_mul_f32 v[126:127], v[110:111], v[126:127] op_sel:[1,0]
	v_pk_fma_f32 v[54:55], v[52:53], v[124:125], v[126:127]
	v_add_f32_dpp v118, v118, v118 quad_perm:[1,0,3,2] row_mask:0xf bank_mask:0xf bound_ctrl:1
	v_add_f32_dpp v119, v119, v119 quad_perm:[1,0,3,2] row_mask:0xf bank_mask:0xf bound_ctrl:1
	s_nop 0
	ds_read_b128 v[120:123], v90 offset:0x5c00
	v_add_f32_dpp v118, v118, v118 quad_perm:[2,3,0,1] row_mask:0xf bank_mask:0xf bound_ctrl:1
	s_nop 0
	ds_read_b128 v[124:127], v90 offset:0x1c00
	v_add_f32_dpp v118, v118, v118 row_half_mirror row_mask:0xf bank_mask:0xf bound_ctrl:1
	s_nop 0
	ds_write2_b32 v93, v1, v119 offset0:72 offset1:108
	v_add_f32_dpp v2, v118, v118 row_mirror row_mask:0xf bank_mask:0xf bound_ctrl:1
	v_add_f32_dpp v118, v118, v118 row_mirror row_mask:0xf bank_mask:0xf bound_ctrl:1
	s_nop 0
	s_waitcnt lgkmcnt(4)
	v_permlane16_swap_b32_e32 v118, v2
	v_add_f32_e32 v118, v118, v2
	v_pk_fma_f32 v[52:53], v[106:107], v[118:119], v[54:55] op_sel_hi:[1,0,1]
	v_pk_mul_f32 v[0:1], v[52:53], v[4:5] op_sel_hi:[0,1]
	v_pk_fma_f32 v[0:1], v[52:53], v[6:7], v[0:1] op_sel:[1,0,0]
	v_pk_mul_f32 v[10:11], v[108:109], v[10:11] op_sel_hi:[0,1]
	v_pk_fma_f32 v[54:55], v[52:53], v[8:9], v[10:11]
	v_add_f32_dpp v0, v0, v0 quad_perm:[1,0,3,2] row_mask:0xf bank_mask:0xf bound_ctrl:1
	v_add_f32_dpp v1, v1, v1 quad_perm:[1,0,3,2] row_mask:0xf bank_mask:0xf bound_ctrl:1
	s_nop 0
	ds_read_b128 v[4:7], v90 offset:0x5e00
	v_add_f32_dpp v0, v0, v0 quad_perm:[2,3,0,1] row_mask:0xf bank_mask:0xf bound_ctrl:1
	s_nop 0
	ds_read_b128 v[8:11], v90 offset:0x1e00
	v_add_f32_dpp v0, v0, v0 row_half_mirror row_mask:0xf bank_mask:0xf bound_ctrl:1
	s_nop 0
	ds_read2st64_b32 v[110:111], v89 offset0:206 offset1:207
	ds_read2st64_b64 v[104:107], v88 offset0:78 offset1:79
	v_add_f32_dpp v2, v0, v0 row_mirror row_mask:0xf bank_mask:0xf bound_ctrl:1
	v_add_f32_dpp v0, v0, v0 row_mirror row_mask:0xf bank_mask:0xf bound_ctrl:1
	s_nop 0
	s_waitcnt lgkmcnt(7)
	v_permlane16_swap_b32_e32 v0, v2
	v_add_f32_e32 v0, v0, v2
	v_pk_fma_f32 v[52:53], v[100:101], v[0:1], v[54:55] op_sel_hi:[1,0,1]
	v_pk_mul_f32 v[118:119], v[52:53], v[112:113] op_sel_hi:[0,1]
	v_pk_fma_f32 v[118:119], v[52:53], v[114:115], v[118:119] op_sel:[1,0,0]
	v_pk_mul_f32 v[98:99], v[108:109], v[98:99] op_sel:[1,0]
	v_pk_fma_f32 v[54:55], v[52:53], v[96:97], v[98:99]
	v_add_f32_dpp v118, v118, v118 quad_perm:[1,0,3,2] row_mask:0xf bank_mask:0xf bound_ctrl:1
	v_add_f32_dpp v119, v119, v119 quad_perm:[1,0,3,2] row_mask:0xf bank_mask:0xf bound_ctrl:1
	s_nop 0
	ds_read_b128 v[112:115], v90 offset:0x6000
	v_add_f32_dpp v118, v118, v118 quad_perm:[2,3,0,1] row_mask:0xf bank_mask:0xf bound_ctrl:1
	s_nop 0
	ds_read_b128 v[96:99], v90 offset:0x2000
	v_add_f32_dpp v118, v118, v118 row_half_mirror row_mask:0xf bank_mask:0xf bound_ctrl:1
	s_nop 0
	ds_write2_b32 v93, v1, v119 offset0:144 offset1:180
	v_add_f32_dpp v2, v118, v118 row_mirror row_mask:0xf bank_mask:0xf bound_ctrl:1
	v_add_f32_dpp v118, v118, v118 row_mirror row_mask:0xf bank_mask:0xf bound_ctrl:1
	s_nop 0
	s_waitcnt lgkmcnt(4)
	v_permlane16_swap_b32_e32 v118, v2
	v_add_f32_e32 v118, v118, v2
	v_pk_fma_f32 v[52:53], v[102:103], v[118:119], v[54:55] op_sel_hi:[1,0,1]
	v_pk_mul_f32 v[0:1], v[52:53], v[120:121] op_sel_hi:[0,1]
	v_pk_fma_f32 v[0:1], v[52:53], v[122:123], v[0:1] op_sel:[1,0,0]
	v_pk_mul_f32 v[126:127], v[110:111], v[126:127] op_sel_hi:[0,1]
	v_pk_fma_f32 v[54:55], v[52:53], v[124:125], v[126:127]
	v_add_f32_dpp v0, v0, v0 quad_perm:[1,0,3,2] row_mask:0xf bank_mask:0xf bound_ctrl:1
	v_add_f32_dpp v1, v1, v1 quad_perm:[1,0,3,2] row_mask:0xf bank_mask:0xf bound_ctrl:1
	s_nop 0
	ds_read_b128 v[120:123], v90 offset:0x6200
	v_add_f32_dpp v0, v0, v0 quad_perm:[2,3,0,1] row_mask:0xf bank_mask:0xf bound_ctrl:1
	s_nop 0
	ds_read_b128 v[124:127], v90 offset:0x2200
	v_add_f32_dpp v0, v0, v0 row_half_mirror row_mask:0xf bank_mask:0xf bound_ctrl:1
	s_nop 0
	ds_read2st64_b32 v[108:109], v89 offset0:208 offset1:209
	ds_read2st64_b64 v[100:103], v88 offset0:80 offset1:81
	v_add_f32_dpp v2, v0, v0 row_mirror row_mask:0xf bank_mask:0xf bound_ctrl:1
	v_add_f32_dpp v0, v0, v0 row_mirror row_mask:0xf bank_mask:0xf bound_ctrl:1
	s_nop 0
	s_waitcnt lgkmcnt(7)
	v_permlane16_swap_b32_e32 v0, v2
	v_add_f32_e32 v0, v0, v2
	v_pk_fma_f32 v[52:53], v[104:105], v[0:1], v[54:55] op_sel_hi:[1,0,1]
	v_pk_mul_f32 v[118:119], v[52:53], v[4:5] op_sel_hi:[0,1]
	v_pk_fma_f32 v[118:119], v[52:53], v[6:7], v[118:119] op_sel:[1,0,0]
	v_pk_mul_f32 v[10:11], v[110:111], v[10:11] op_sel:[1,0]
	v_pk_fma_f32 v[54:55], v[52:53], v[8:9], v[10:11]
	v_add_f32_dpp v118, v118, v118 quad_perm:[1,0,3,2] row_mask:0xf bank_mask:0xf bound_ctrl:1
	v_add_f32_dpp v119, v119, v119 quad_perm:[1,0,3,2] row_mask:0xf bank_mask:0xf bound_ctrl:1
	s_nop 0
	ds_read_b128 v[4:7], v90 offset:0x6400
	v_add_f32_dpp v118, v118, v118 quad_perm:[2,3,0,1] row_mask:0xf bank_mask:0xf bound_ctrl:1
	s_nop 0
	ds_read_b128 v[8:11], v90 offset:0x2400
	v_add_f32_dpp v118, v118, v118 row_half_mirror row_mask:0xf bank_mask:0xf bound_ctrl:1
	s_nop 0
	ds_write2_b32 v93, v1, v119 offset0:216 offset1:252
	v_add_f32_dpp v2, v118, v118 row_mirror row_mask:0xf bank_mask:0xf bound_ctrl:1
	v_add_f32_dpp v118, v118, v118 row_mirror row_mask:0xf bank_mask:0xf bound_ctrl:1
	s_nop 0
	s_waitcnt lgkmcnt(4)
	v_permlane16_swap_b32_e32 v118, v2
	v_add_f32_e32 v118, v118, v2
	v_pk_fma_f32 v[52:53], v[106:107], v[118:119], v[54:55] op_sel_hi:[1,0,1]
	s_cmp_eq_u32 s88, 0x800000
	s_cbranch_scc1 .LBB0_684
	v_pk_mul_f32 v[0:1], v[52:53], v[112:113] op_sel_hi:[0,1]
	v_pk_fma_f32 v[0:1], v[52:53], v[114:115], v[0:1] op_sel:[1,0,0]
	v_pk_mul_f32 v[98:99], v[108:109], v[98:99] op_sel_hi:[0,1]
	v_pk_fma_f32 v[54:55], v[52:53], v[96:97], v[98:99]
	v_add_f32_dpp v0, v0, v0 quad_perm:[1,0,3,2] row_mask:0xf bank_mask:0xf bound_ctrl:1
	v_add_f32_dpp v1, v1, v1 quad_perm:[1,0,3,2] row_mask:0xf bank_mask:0xf bound_ctrl:1
	s_nop 0
	ds_read_b128 v[112:115], v90 offset:0x6600
	v_add_f32_dpp v0, v0, v0 quad_perm:[2,3,0,1] row_mask:0xf bank_mask:0xf bound_ctrl:1
	s_nop 0
	ds_read_b128 v[96:99], v90 offset:0x2600
	v_add_f32_dpp v0, v0, v0 row_half_mirror row_mask:0xf bank_mask:0xf bound_ctrl:1
	s_nop 0
	ds_read2st64_b32 v[110:111], v89 offset0:210 offset1:211
	ds_read2st64_b64 v[104:107], v88 offset0:82 offset1:83
	v_add_f32_dpp v2, v0, v0 row_mirror row_mask:0xf bank_mask:0xf bound_ctrl:1
	v_add_f32_dpp v0, v0, v0 row_mirror row_mask:0xf bank_mask:0xf bound_ctrl:1
	v_add_u32_e32 v93, 0x480, v93
	s_waitcnt lgkmcnt(7)
	v_permlane16_swap_b32_e32 v0, v2
	v_add_f32_e32 v0, v0, v2
	v_pk_fma_f32 v[52:53], v[100:101], v[0:1], v[54:55] op_sel_hi:[1,0,1]
	v_pk_mul_f32 v[118:119], v[52:53], v[120:121] op_sel_hi:[0,1]
	v_pk_fma_f32 v[118:119], v[52:53], v[122:123], v[118:119] op_sel:[1,0,0]
	v_pk_mul_f32 v[126:127], v[108:109], v[126:127] op_sel:[1,0]
	v_pk_fma_f32 v[54:55], v[52:53], v[124:125], v[126:127]
	v_add_f32_dpp v118, v118, v118 quad_perm:[1,0,3,2] row_mask:0xf bank_mask:0xf bound_ctrl:1
	v_add_f32_dpp v119, v119, v119 quad_perm:[1,0,3,2] row_mask:0xf bank_mask:0xf bound_ctrl:1
	s_nop 0
	ds_read_b128 v[120:123], v90 offset:0x6800
	v_add_f32_dpp v118, v118, v118 quad_perm:[2,3,0,1] row_mask:0xf bank_mask:0xf bound_ctrl:1
	s_nop 0
	ds_read_b128 v[124:127], v90 offset:0x2800
	v_add_f32_dpp v118, v118, v118 row_half_mirror row_mask:0xf bank_mask:0xf bound_ctrl:1
	s_nop 0
	ds_write2_b32 v93, v1, v119 offset0:0 offset1:36
	v_add_f32_dpp v2, v118, v118 row_mirror row_mask:0xf bank_mask:0xf bound_ctrl:1
	v_add_f32_dpp v118, v118, v118 row_mirror row_mask:0xf bank_mask:0xf bound_ctrl:1
	s_nop 0
	s_waitcnt lgkmcnt(4)
	v_permlane16_swap_b32_e32 v118, v2
	v_add_f32_e32 v118, v118, v2
	v_pk_fma_f32 v[52:53], v[102:103], v[118:119], v[54:55] op_sel_hi:[1,0,1]
	v_pk_mul_f32 v[0:1], v[52:53], v[4:5] op_sel_hi:[0,1]
	v_pk_fma_f32 v[0:1], v[52:53], v[6:7], v[0:1] op_sel:[1,0,0]
	v_pk_mul_f32 v[10:11], v[110:111], v[10:11] op_sel_hi:[0,1]
	v_pk_fma_f32 v[54:55], v[52:53], v[8:9], v[10:11]
	v_add_f32_dpp v0, v0, v0 quad_perm:[1,0,3,2] row_mask:0xf bank_mask:0xf bound_ctrl:1
	v_add_f32_dpp v1, v1, v1 quad_perm:[1,0,3,2] row_mask:0xf bank_mask:0xf bound_ctrl:1
	s_nop 0
	ds_read_b128 v[4:7], v90 offset:0x6a00
	v_add_f32_dpp v0, v0, v0 quad_perm:[2,3,0,1] row_mask:0xf bank_mask:0xf bound_ctrl:1
	s_nop 0
	ds_read_b128 v[8:11], v90 offset:0x2a00
	v_add_f32_dpp v0, v0, v0 row_half_mirror row_mask:0xf bank_mask:0xf bound_ctrl:1
	s_nop 0
	ds_read2st64_b32 v[108:109], v89 offset0:212 offset1:213
	ds_read2st64_b64 v[100:103], v88 offset0:84 offset1:85
	v_add_f32_dpp v2, v0, v0 row_mirror row_mask:0xf bank_mask:0xf bound_ctrl:1
	v_add_f32_dpp v0, v0, v0 row_mirror row_mask:0xf bank_mask:0xf bound_ctrl:1
	s_nop 0
	s_waitcnt lgkmcnt(7)
	v_permlane16_swap_b32_e32 v0, v2
	v_add_f32_e32 v0, v0, v2
	v_pk_fma_f32 v[52:53], v[104:105], v[0:1], v[54:55] op_sel_hi:[1,0,1]
	v_pk_mul_f32 v[118:119], v[52:53], v[112:113] op_sel_hi:[0,1]
	v_pk_fma_f32 v[118:119], v[52:53], v[114:115], v[118:119] op_sel:[1,0,0]
	v_pk_mul_f32 v[98:99], v[110:111], v[98:99] op_sel:[1,0]
	v_pk_fma_f32 v[54:55], v[52:53], v[96:97], v[98:99]
	v_add_f32_dpp v118, v118, v118 quad_perm:[1,0,3,2] row_mask:0xf bank_mask:0xf bound_ctrl:1
	v_add_f32_dpp v119, v119, v119 quad_perm:[1,0,3,2] row_mask:0xf bank_mask:0xf bound_ctrl:1
	s_nop 0
	ds_read_b128 v[112:115], v90 offset:0x6c00
	v_add_f32_dpp v118, v118, v118 quad_perm:[2,3,0,1] row_mask:0xf bank_mask:0xf bound_ctrl:1
	s_nop 0
	ds_read_b128 v[96:99], v90 offset:0x2c00
	v_add_f32_dpp v118, v118, v118 row_half_mirror row_mask:0xf bank_mask:0xf bound_ctrl:1
	s_nop 0
	ds_write2_b32 v93, v1, v119 offset0:72 offset1:108
	v_add_f32_dpp v2, v118, v118 row_mirror row_mask:0xf bank_mask:0xf bound_ctrl:1
	v_add_f32_dpp v118, v118, v118 row_mirror row_mask:0xf bank_mask:0xf bound_ctrl:1
	s_nop 0
	s_waitcnt lgkmcnt(4)
	v_permlane16_swap_b32_e32 v118, v2
	v_add_f32_e32 v118, v118, v2
	v_pk_fma_f32 v[52:53], v[106:107], v[118:119], v[54:55] op_sel_hi:[1,0,1]
	v_pk_mul_f32 v[0:1], v[52:53], v[120:121] op_sel_hi:[0,1]
	v_pk_fma_f32 v[0:1], v[52:53], v[122:123], v[0:1] op_sel:[1,0,0]
	v_pk_mul_f32 v[126:127], v[108:109], v[126:127] op_sel_hi:[0,1]
	v_pk_fma_f32 v[54:55], v[52:53], v[124:125], v[126:127]
	v_add_f32_dpp v0, v0, v0 quad_perm:[1,0,3,2] row_mask:0xf bank_mask:0xf bound_ctrl:1
	v_add_f32_dpp v1, v1, v1 quad_perm:[1,0,3,2] row_mask:0xf bank_mask:0xf bound_ctrl:1
	s_nop 0
	ds_read_b128 v[120:123], v90 offset:0x6e00
	v_add_f32_dpp v0, v0, v0 quad_perm:[2,3,0,1] row_mask:0xf bank_mask:0xf bound_ctrl:1
	s_nop 0
	ds_read_b128 v[124:127], v90 offset:0x2e00
	v_add_f32_dpp v0, v0, v0 row_half_mirror row_mask:0xf bank_mask:0xf bound_ctrl:1
	s_nop 0
	ds_read2st64_b32 v[110:111], v89 offset0:214 offset1:215
	ds_read2st64_b64 v[104:107], v88 offset0:86 offset1:87
	v_add_f32_dpp v2, v0, v0 row_mirror row_mask:0xf bank_mask:0xf bound_ctrl:1
	v_add_f32_dpp v0, v0, v0 row_mirror row_mask:0xf bank_mask:0xf bound_ctrl:1
	s_nop 0
	s_waitcnt lgkmcnt(7)
	v_permlane16_swap_b32_e32 v0, v2
	v_add_f32_e32 v0, v0, v2
	v_pk_fma_f32 v[52:53], v[100:101], v[0:1], v[54:55] op_sel_hi:[1,0,1]
	v_pk_mul_f32 v[118:119], v[52:53], v[4:5] op_sel_hi:[0,1]
	v_pk_fma_f32 v[118:119], v[52:53], v[6:7], v[118:119] op_sel:[1,0,0]
	v_pk_mul_f32 v[10:11], v[108:109], v[10:11] op_sel:[1,0]
	v_pk_fma_f32 v[54:55], v[52:53], v[8:9], v[10:11]
	v_add_f32_dpp v118, v118, v118 quad_perm:[1,0,3,2] row_mask:0xf bank_mask:0xf bound_ctrl:1
	v_add_f32_dpp v119, v119, v119 quad_perm:[1,0,3,2] row_mask:0xf bank_mask:0xf bound_ctrl:1
	s_nop 0
	ds_read_b128 v[4:7], v90 offset:0x7000
	v_add_f32_dpp v118, v118, v118 quad_perm:[2,3,0,1] row_mask:0xf bank_mask:0xf bound_ctrl:1
	s_nop 0
	ds_read_b128 v[8:11], v90 offset:0x3000
	v_add_f32_dpp v118, v118, v118 row_half_mirror row_mask:0xf bank_mask:0xf bound_ctrl:1
	s_nop 0
	ds_write2_b32 v93, v1, v119 offset0:144 offset1:180
	v_add_f32_dpp v2, v118, v118 row_mirror row_mask:0xf bank_mask:0xf bound_ctrl:1
	v_add_f32_dpp v118, v118, v118 row_mirror row_mask:0xf bank_mask:0xf bound_ctrl:1
	s_nop 0
	s_waitcnt lgkmcnt(4)
	v_permlane16_swap_b32_e32 v118, v2
	v_add_f32_e32 v118, v118, v2
	v_pk_fma_f32 v[52:53], v[102:103], v[118:119], v[54:55] op_sel_hi:[1,0,1]
	v_pk_mul_f32 v[0:1], v[52:53], v[112:113] op_sel_hi:[0,1]
	v_pk_fma_f32 v[0:1], v[52:53], v[114:115], v[0:1] op_sel:[1,0,0]
	v_pk_mul_f32 v[98:99], v[110:111], v[98:99] op_sel_hi:[0,1]
	v_pk_fma_f32 v[54:55], v[52:53], v[96:97], v[98:99]
	v_add_f32_dpp v0, v0, v0 quad_perm:[1,0,3,2] row_mask:0xf bank_mask:0xf bound_ctrl:1
	v_add_f32_dpp v1, v1, v1 quad_perm:[1,0,3,2] row_mask:0xf bank_mask:0xf bound_ctrl:1
	s_nop 0
	ds_read_b128 v[112:115], v90 offset:0x7200
	v_add_f32_dpp v0, v0, v0 quad_perm:[2,3,0,1] row_mask:0xf bank_mask:0xf bound_ctrl:1
	s_nop 0
	ds_read_b128 v[96:99], v90 offset:0x3200
	v_add_f32_dpp v0, v0, v0 row_half_mirror row_mask:0xf bank_mask:0xf bound_ctrl:1
	s_nop 0
	ds_read2st64_b32 v[108:109], v89 offset0:216 offset1:217
	ds_read2st64_b64 v[100:103], v88 offset0:88 offset1:89
	v_add_f32_dpp v2, v0, v0 row_mirror row_mask:0xf bank_mask:0xf bound_ctrl:1
	v_add_f32_dpp v0, v0, v0 row_mirror row_mask:0xf bank_mask:0xf bound_ctrl:1
	s_nop 0
	s_waitcnt lgkmcnt(7)
	v_permlane16_swap_b32_e32 v0, v2
	v_add_f32_e32 v0, v0, v2
	v_pk_fma_f32 v[52:53], v[104:105], v[0:1], v[54:55] op_sel_hi:[1,0,1]
	v_pk_mul_f32 v[118:119], v[52:53], v[120:121] op_sel_hi:[0,1]
	v_pk_fma_f32 v[118:119], v[52:53], v[122:123], v[118:119] op_sel:[1,0,0]
	v_pk_mul_f32 v[126:127], v[110:111], v[126:127] op_sel:[1,0]
	v_pk_fma_f32 v[54:55], v[52:53], v[124:125], v[126:127]
	v_add_f32_dpp v118, v118, v118 quad_perm:[1,0,3,2] row_mask:0xf bank_mask:0xf bound_ctrl:1
	v_add_f32_dpp v119, v119, v119 quad_perm:[1,0,3,2] row_mask:0xf bank_mask:0xf bound_ctrl:1
	s_nop 0
	ds_read_b128 v[120:123], v90 offset:0x7400
	v_add_f32_dpp v118, v118, v118 quad_perm:[2,3,0,1] row_mask:0xf bank_mask:0xf bound_ctrl:1
	s_nop 0
	ds_read_b128 v[124:127], v90 offset:0x3400
	v_add_f32_dpp v118, v118, v118 row_half_mirror row_mask:0xf bank_mask:0xf bound_ctrl:1
	s_nop 0
	ds_write2_b32 v93, v1, v119 offset0:216 offset1:252
	v_add_f32_dpp v2, v118, v118 row_mirror row_mask:0xf bank_mask:0xf bound_ctrl:1
	v_add_f32_dpp v118, v118, v118 row_mirror row_mask:0xf bank_mask:0xf bound_ctrl:1
	s_nop 0
	s_waitcnt lgkmcnt(4)
	v_permlane16_swap_b32_e32 v118, v2
	v_add_f32_e32 v118, v118, v2
	v_pk_fma_f32 v[52:53], v[106:107], v[118:119], v[54:55] op_sel_hi:[1,0,1]
	v_pk_mul_f32 v[0:1], v[52:53], v[4:5] op_sel_hi:[0,1]
	v_pk_fma_f32 v[0:1], v[52:53], v[6:7], v[0:1] op_sel:[1,0,0]
	v_pk_mul_f32 v[10:11], v[108:109], v[10:11] op_sel_hi:[0,1]
	v_pk_fma_f32 v[54:55], v[52:53], v[8:9], v[10:11]
	v_add_f32_dpp v0, v0, v0 quad_perm:[1,0,3,2] row_mask:0xf bank_mask:0xf bound_ctrl:1
	v_add_f32_dpp v1, v1, v1 quad_perm:[1,0,3,2] row_mask:0xf bank_mask:0xf bound_ctrl:1
	s_nop 0
	ds_read_b128 v[4:7], v90 offset:0x7600
	v_add_f32_dpp v0, v0, v0 quad_perm:[2,3,0,1] row_mask:0xf bank_mask:0xf bound_ctrl:1
	s_nop 0
	ds_read_b128 v[8:11], v90 offset:0x3600
	v_add_f32_dpp v0, v0, v0 row_half_mirror row_mask:0xf bank_mask:0xf bound_ctrl:1
	s_nop 0
	ds_read2st64_b32 v[110:111], v89 offset0:218 offset1:219
	ds_read2st64_b64 v[104:107], v88 offset0:90 offset1:91
	v_add_f32_dpp v2, v0, v0 row_mirror row_mask:0xf bank_mask:0xf bound_ctrl:1
	v_add_f32_dpp v0, v0, v0 row_mirror row_mask:0xf bank_mask:0xf bound_ctrl:1
	v_add_u32_e32 v93, 0x480, v93
	s_waitcnt lgkmcnt(7)
	v_permlane16_swap_b32_e32 v0, v2
	v_add_f32_e32 v0, v0, v2
	v_pk_fma_f32 v[52:53], v[100:101], v[0:1], v[54:55] op_sel_hi:[1,0,1]
	v_pk_mul_f32 v[118:119], v[52:53], v[112:113] op_sel_hi:[0,1]
	v_pk_fma_f32 v[118:119], v[52:53], v[114:115], v[118:119] op_sel:[1,0,0]
	v_pk_mul_f32 v[98:99], v[108:109], v[98:99] op_sel:[1,0]
	v_pk_fma_f32 v[54:55], v[52:53], v[96:97], v[98:99]
	v_add_f32_dpp v118, v118, v118 quad_perm:[1,0,3,2] row_mask:0xf bank_mask:0xf bound_ctrl:1
	v_add_f32_dpp v119, v119, v119 quad_perm:[1,0,3,2] row_mask:0xf bank_mask:0xf bound_ctrl:1
	s_nop 0
	ds_read_b128 v[112:115], v90 offset:0x7800
	v_add_f32_dpp v118, v118, v118 quad_perm:[2,3,0,1] row_mask:0xf bank_mask:0xf bound_ctrl:1
	s_nop 0
	ds_read_b128 v[96:99], v90 offset:0x3800
	v_add_f32_dpp v118, v118, v118 row_half_mirror row_mask:0xf bank_mask:0xf bound_ctrl:1
	s_nop 0
	ds_write2_b32 v93, v1, v119 offset0:0 offset1:36
	v_add_f32_dpp v2, v118, v118 row_mirror row_mask:0xf bank_mask:0xf bound_ctrl:1
	v_add_f32_dpp v118, v118, v118 row_mirror row_mask:0xf bank_mask:0xf bound_ctrl:1
	s_nop 0
	s_waitcnt lgkmcnt(4)
	v_permlane16_swap_b32_e32 v118, v2
	v_add_f32_e32 v118, v118, v2
	v_pk_fma_f32 v[52:53], v[102:103], v[118:119], v[54:55] op_sel_hi:[1,0,1]
	v_pk_mul_f32 v[0:1], v[52:53], v[120:121] op_sel_hi:[0,1]
	v_pk_fma_f32 v[0:1], v[52:53], v[122:123], v[0:1] op_sel:[1,0,0]
	v_pk_mul_f32 v[126:127], v[110:111], v[126:127] op_sel_hi:[0,1]
	v_pk_fma_f32 v[54:55], v[52:53], v[124:125], v[126:127]
	v_add_f32_dpp v0, v0, v0 quad_perm:[1,0,3,2] row_mask:0xf bank_mask:0xf bound_ctrl:1
	v_add_f32_dpp v1, v1, v1 quad_perm:[1,0,3,2] row_mask:0xf bank_mask:0xf bound_ctrl:1
	s_nop 0
	ds_read_b128 v[120:123], v90 offset:0x7a00
	v_add_f32_dpp v0, v0, v0 quad_perm:[2,3,0,1] row_mask:0xf bank_mask:0xf bound_ctrl:1
	s_nop 0
	ds_read_b128 v[124:127], v90 offset:0x3a00
	v_add_f32_dpp v0, v0, v0 row_half_mirror row_mask:0xf bank_mask:0xf bound_ctrl:1
	s_nop 0
	ds_read2st64_b32 v[108:109], v89 offset0:220 offset1:221
	ds_read2st64_b64 v[100:103], v88 offset0:92 offset1:93
	v_add_f32_dpp v2, v0, v0 row_mirror row_mask:0xf bank_mask:0xf bound_ctrl:1
	v_add_f32_dpp v0, v0, v0 row_mirror row_mask:0xf bank_mask:0xf bound_ctrl:1
	s_nop 0
	s_waitcnt lgkmcnt(7)
	v_permlane16_swap_b32_e32 v0, v2
	v_add_f32_e32 v0, v0, v2
	v_pk_fma_f32 v[52:53], v[104:105], v[0:1], v[54:55] op_sel_hi:[1,0,1]
	v_pk_mul_f32 v[118:119], v[52:53], v[4:5] op_sel_hi:[0,1]
	v_pk_fma_f32 v[118:119], v[52:53], v[6:7], v[118:119] op_sel:[1,0,0]
	v_pk_mul_f32 v[10:11], v[110:111], v[10:11] op_sel:[1,0]
	v_pk_fma_f32 v[54:55], v[52:53], v[8:9], v[10:11]
	v_add_f32_dpp v118, v118, v118 quad_perm:[1,0,3,2] row_mask:0xf bank_mask:0xf bound_ctrl:1
	v_add_f32_dpp v119, v119, v119 quad_perm:[1,0,3,2] row_mask:0xf bank_mask:0xf bound_ctrl:1
	s_nop 0
	ds_read_b128 v[4:7], v90 offset:0x7c00
	v_add_f32_dpp v118, v118, v118 quad_perm:[2,3,0,1] row_mask:0xf bank_mask:0xf bound_ctrl:1
	s_nop 0
	ds_read_b128 v[8:11], v90 offset:0x3c00
	v_add_f32_dpp v118, v118, v118 row_half_mirror row_mask:0xf bank_mask:0xf bound_ctrl:1
	s_nop 0
	ds_write2_b32 v93, v1, v119 offset0:72 offset1:108
	v_add_f32_dpp v2, v118, v118 row_mirror row_mask:0xf bank_mask:0xf bound_ctrl:1
	v_add_f32_dpp v118, v118, v118 row_mirror row_mask:0xf bank_mask:0xf bound_ctrl:1
	s_nop 0
	s_waitcnt lgkmcnt(4)
	v_permlane16_swap_b32_e32 v118, v2
	v_add_f32_e32 v118, v118, v2
	v_pk_fma_f32 v[52:53], v[106:107], v[118:119], v[54:55] op_sel_hi:[1,0,1]
	v_pk_mul_f32 v[0:1], v[52:53], v[112:113] op_sel_hi:[0,1]
	v_pk_fma_f32 v[0:1], v[52:53], v[114:115], v[0:1] op_sel:[1,0,0]
	v_pk_mul_f32 v[98:99], v[108:109], v[98:99] op_sel_hi:[0,1]
	v_pk_fma_f32 v[54:55], v[52:53], v[96:97], v[98:99]
	v_add_f32_dpp v0, v0, v0 quad_perm:[1,0,3,2] row_mask:0xf bank_mask:0xf bound_ctrl:1
	v_add_f32_dpp v1, v1, v1 quad_perm:[1,0,3,2] row_mask:0xf bank_mask:0xf bound_ctrl:1
	s_nop 0
	ds_read_b128 v[112:115], v90 offset:0x7e00
	v_add_f32_dpp v0, v0, v0 quad_perm:[2,3,0,1] row_mask:0xf bank_mask:0xf bound_ctrl:1
	s_nop 0
	ds_read_b128 v[96:99], v90 offset:0x3e00
	v_add_f32_dpp v0, v0, v0 row_half_mirror row_mask:0xf bank_mask:0xf bound_ctrl:1
	s_nop 0
	ds_read2st64_b32 v[110:111], v89 offset0:222 offset1:223
	ds_read2st64_b64 v[104:107], v88 offset0:94 offset1:95
	v_add_f32_dpp v2, v0, v0 row_mirror row_mask:0xf bank_mask:0xf bound_ctrl:1
	v_add_f32_dpp v0, v0, v0 row_mirror row_mask:0xf bank_mask:0xf bound_ctrl:1
	s_nop 0
	s_waitcnt lgkmcnt(7)
	v_permlane16_swap_b32_e32 v0, v2
	v_add_f32_e32 v0, v0, v2
	v_pk_fma_f32 v[52:53], v[100:101], v[0:1], v[54:55] op_sel_hi:[1,0,1]
	v_pk_mul_f32 v[118:119], v[52:53], v[120:121] op_sel_hi:[0,1]
	v_pk_fma_f32 v[118:119], v[52:53], v[122:123], v[118:119] op_sel:[1,0,0]
	v_pk_mul_f32 v[126:127], v[108:109], v[126:127] op_sel:[1,0]
	v_pk_fma_f32 v[54:55], v[52:53], v[124:125], v[126:127]
	v_add_f32_dpp v118, v118, v118 quad_perm:[1,0,3,2] row_mask:0xf bank_mask:0xf bound_ctrl:1
	v_add_f32_dpp v119, v119, v119 quad_perm:[1,0,3,2] row_mask:0xf bank_mask:0xf bound_ctrl:1
	s_nop 0
	s_nop 0
	v_add_f32_dpp v118, v118, v118 quad_perm:[2,3,0,1] row_mask:0xf bank_mask:0xf bound_ctrl:1
	s_nop 0
	s_nop 0
	v_add_f32_dpp v118, v118, v118 row_half_mirror row_mask:0xf bank_mask:0xf bound_ctrl:1
	s_nop 0
	ds_write2_b32 v93, v1, v119 offset0:144 offset1:180
	v_add_f32_dpp v2, v118, v118 row_mirror row_mask:0xf bank_mask:0xf bound_ctrl:1
	v_add_f32_dpp v118, v118, v118 row_mirror row_mask:0xf bank_mask:0xf bound_ctrl:1
	s_nop 0
	s_waitcnt lgkmcnt(2)
	v_permlane16_swap_b32_e32 v118, v2
	v_add_f32_e32 v118, v118, v2
	v_pk_fma_f32 v[52:53], v[102:103], v[118:119], v[54:55] op_sel_hi:[1,0,1]
	v_pk_mul_f32 v[0:1], v[52:53], v[4:5] op_sel_hi:[0,1]
	v_pk_fma_f32 v[0:1], v[52:53], v[6:7], v[0:1] op_sel:[1,0,0]
	v_pk_mul_f32 v[10:11], v[110:111], v[10:11] op_sel_hi:[0,1]
	v_pk_fma_f32 v[54:55], v[52:53], v[8:9], v[10:11]
	v_add_f32_dpp v0, v0, v0 quad_perm:[1,0,3,2] row_mask:0xf bank_mask:0xf bound_ctrl:1
	v_add_f32_dpp v1, v1, v1 quad_perm:[1,0,3,2] row_mask:0xf bank_mask:0xf bound_ctrl:1
	s_nop 0
	s_nop 0
	v_add_f32_dpp v0, v0, v0 quad_perm:[2,3,0,1] row_mask:0xf bank_mask:0xf bound_ctrl:1
	s_nop 0
	s_nop 0
	v_add_f32_dpp v0, v0, v0 row_half_mirror row_mask:0xf bank_mask:0xf bound_ctrl:1
	s_nop 0
	s_nop 0
	v_add_f32_dpp v2, v0, v0 row_mirror row_mask:0xf bank_mask:0xf bound_ctrl:1
	v_add_f32_dpp v0, v0, v0 row_mirror row_mask:0xf bank_mask:0xf bound_ctrl:1
	s_nop 0
	s_waitcnt lgkmcnt(1)
	v_permlane16_swap_b32_e32 v0, v2
	v_add_f32_e32 v0, v0, v2
	v_pk_fma_f32 v[52:53], v[104:105], v[0:1], v[54:55] op_sel_hi:[1,0,1]
	v_pk_mul_f32 v[118:119], v[52:53], v[112:113] op_sel_hi:[0,1]
	v_pk_fma_f32 v[118:119], v[52:53], v[114:115], v[118:119] op_sel:[1,0,0]
	v_pk_mul_f32 v[98:99], v[110:111], v[98:99] op_sel:[1,0]
	v_pk_fma_f32 v[54:55], v[52:53], v[96:97], v[98:99]
	v_add_f32_dpp v118, v118, v118 quad_perm:[1,0,3,2] row_mask:0xf bank_mask:0xf bound_ctrl:1
	v_add_f32_dpp v119, v119, v119 quad_perm:[1,0,3,2] row_mask:0xf bank_mask:0xf bound_ctrl:1
	s_nop 0
	s_nop 0
	v_add_f32_dpp v118, v118, v118 quad_perm:[2,3,0,1] row_mask:0xf bank_mask:0xf bound_ctrl:1
	s_nop 0
	s_nop 0
	v_add_f32_dpp v118, v118, v118 row_half_mirror row_mask:0xf bank_mask:0xf bound_ctrl:1
	s_nop 0
	ds_write2_b32 v93, v1, v119 offset0:216 offset1:252
	v_add_f32_dpp v2, v118, v118 row_mirror row_mask:0xf bank_mask:0xf bound_ctrl:1
	v_add_f32_dpp v118, v118, v118 row_mirror row_mask:0xf bank_mask:0xf bound_ctrl:1
	s_nop 0
	s_nop 0
	v_permlane16_swap_b32_e32 v118, v2
	v_add_f32_e32 v118, v118, v2
	v_pk_fma_f32 v[52:53], v[106:107], v[118:119], v[54:55] op_sel_hi:[1,0,1]
